# P2x state update: kt-block LDS reads double-buffered one block ahead (block 0 at the head of the U chain)
# baseline (speedup 1.0000x reference)
.LBB0_576:
	v_add_u32_e32 v57, v164, v165
	ds_read_b128 v[212:215], v182 offset:13568
	ds_read_b32 v228, v57 offset:13568
	ds_read_u16 v236, v49 offset:4608
	ds_read_u16 v237, v49 offset:4752
	ds_read_u16 v238, v49 offset:4896
	ds_read_u16 v239, v49 offset:5040
	s_and_b64 vcc, exec, s[40:41]
	s_cbranch_vccnz .Lktr0
	ds_read_u16 v240, v49 offset:6912
	ds_read_u16 v241, v49 offset:7056
	ds_read_u16 v242, v49 offset:7200
	ds_read_u16 v243, v49 offset:7344
.Lktr0:
	v_cndmask_b32_e64 v16, 0, v32, s[24:25]
	v_cndmask_b32_e64 v17, 0, v33, s[30:31]
	v_cndmask_b32_e64 v18, 0, v34, s[34:35]
	v_cndmask_b32_e64 v19, 0, v35, s[36:37]
	v_cvt_pk_bf16_f32 v28, v16, v17
	v_cvt_pk_bf16_f32 v29, v18, v19
	v_cndmask_b32_e64 v20, 0, v36, s[22:23]
	v_cndmask_b32_e64 v21, v37, 0, s[24:25]
	v_cndmask_b32_e64 v22, 0, v38, s[26:27]
	v_cndmask_b32_e64 v23, 0, v39, s[28:29]
	v_cvt_pk_bf16_f32 v16, v24, v25
	v_cvt_pk_bf16_f32 v17, v26, v27
	v_add_u32_e32 v143, 0, v182
	v_add_u32_e32 v144, v164, v165
	v_mfma_f32_16x16x16_bf16 v[16:19], v[28:29], v[16:17], v[24:27]
	s_and_b64 vcc, exec, s[40:41]
	s_nop 1
	v_cvt_pk_bf16_f32 v24, v20, v21
	v_cvt_pk_bf16_f32 v25, v22, v23
	s_nop 1
	v_mfma_f32_16x16x16_bf16 v[20:23], v[28:29], v[24:25], 0
	v_mfma_f32_16x16x16_bf16 v[24:27], v[24:25], v[28:29], 0
	s_nop 7
	v_cvt_pk_bf16_f32 v24, v24, v25
	v_cvt_pk_bf16_f32 v25, v26, v27
	v_cvt_pk_bf16_f32 v26, v16, v17
	v_cvt_pk_bf16_f32 v27, v18, v19
	s_nop 1
	v_mfma_f32_16x16x16_bf16 v[16:19], v[24:25], v[26:27], v[16:19]
	v_cvt_pk_bf16_f32 v26, v20, v21
	v_cvt_pk_bf16_f32 v27, v22, v23
	s_nop 1
	v_mfma_f32_16x16x16_bf16 v[20:23], v[24:25], v[26:27], 0
	v_mfma_f32_16x16x16_bf16 v[24:27], v[26:27], v[24:25], 0
	s_nop 6
	v_cvt_pk_bf16_f32 v20, v20, v21
	v_cvt_pk_bf16_f32 v21, v22, v23
	v_cvt_pk_bf16_f32 v24, v24, v25
	v_cvt_pk_bf16_f32 v25, v26, v27
	v_cvt_pk_bf16_f32 v26, v16, v17
	v_cvt_pk_bf16_f32 v27, v18, v19
	v_mfma_f32_16x16x16_bf16 v[20:23], v[20:21], v[24:25], 0
	s_nop 0
	v_mfma_f32_16x16x16_bf16 v[16:19], v[24:25], v[26:27], v[16:19]
	s_nop 5
	v_cvt_pk_bf16_f32 v20, v20, v21
	v_cvt_pk_bf16_f32 v21, v22, v23
	v_cvt_pk_bf16_f32 v22, v16, v17
	v_cvt_pk_bf16_f32 v23, v18, v19
	s_nop 1
	v_mfma_f32_16x16x16_bf16 v[16:19], v[20:21], v[22:23], v[16:19]
	s_nop 7
	v_cvt_pk_bf16_f32 v16, v16, v17
	v_cvt_pk_bf16_f32 v17, v18, v19
	s_and_b64 vcc, exec, s[40:41]
	s_cbranch_vccnz .Lkt0_nov
	s_waitcnt lgkmcnt(0)
	ds_read_b128 v[216:219], v182 offset:13632
	ds_read_b32 v230, v57 offset:13632
	ds_read_u16 v244, v49 offset:4640
	ds_read_u16 v245, v49 offset:4784
	ds_read_u16 v246, v49 offset:4928
	ds_read_u16 v247, v49 offset:5072
	ds_read_u16 v220, v49 offset:6944
	ds_read_u16 v221, v49 offset:7088
	ds_read_u16 v222, v49 offset:7232
	ds_read_u16 v223, v49 offset:7376
	v_pk_mul_f32 v[12:13], v[12:13], v[212:213]
	v_pk_mul_f32 v[14:15], v[14:15], v[214:215]
	v_lshlrev_b32_e32 v236, 16, v236
	v_lshlrev_b32_e32 v237, 16, v237
	v_lshlrev_b32_e32 v238, 16, v238
	v_lshlrev_b32_e32 v239, 16, v239
	v_pk_mul_f32 v[236:237], v[228:229], v[236:237] op_sel_hi:[0,1]
	v_pk_mul_f32 v[238:239], v[228:229], v[238:239] op_sel_hi:[0,1]
	v_cvt_pk_bf16_f32 v236, v236, v237
	v_cvt_pk_bf16_f32 v237, v238, v239
	v_lshlrev_b32_e32 v240, 16, v240
	v_lshlrev_b32_e32 v241, 16, v241
	v_mfma_f32_16x16x16_bf16 v[12:15], v[236:237], v[16:17], v[12:15]
	v_lshlrev_b32_e32 v242, 16, v242
	v_lshlrev_b32_e32 v243, 16, v243
	v_pk_mul_f32 v[240:241], v[228:229], v[240:241] op_sel_hi:[0,1]
	v_pk_mul_f32 v[242:243], v[228:229], v[242:243] op_sel_hi:[0,1]
	v_cvt_pk_bf16_f32 v240, v240, v241
	v_cvt_pk_bf16_f32 v241, v242, v243
	s_nop 1
	v_mfma_f32_16x16x16_bf16 v[12:15], v[240:241], v[98:99], v[12:15]
	s_waitcnt lgkmcnt(0)
	ds_read_b128 v[212:215], v182 offset:13696
	ds_read_b32 v228, v57 offset:13696
	ds_read_u16 v236, v49 offset:4672
	ds_read_u16 v237, v49 offset:4816
	ds_read_u16 v238, v49 offset:4960
	ds_read_u16 v239, v49 offset:5104
	ds_read_u16 v240, v49 offset:6976
	ds_read_u16 v241, v49 offset:7120
	ds_read_u16 v242, v49 offset:7264
	ds_read_u16 v243, v49 offset:7408
	v_pk_mul_f32 v[8:9], v[8:9], v[216:217]
	v_pk_mul_f32 v[10:11], v[10:11], v[218:219]
	v_lshlrev_b32_e32 v244, 16, v244
	v_lshlrev_b32_e32 v245, 16, v245
	v_lshlrev_b32_e32 v246, 16, v246
	v_lshlrev_b32_e32 v247, 16, v247
	v_pk_mul_f32 v[244:245], v[230:231], v[244:245] op_sel_hi:[0,1]
	v_pk_mul_f32 v[246:247], v[230:231], v[246:247] op_sel_hi:[0,1]
	v_cvt_pk_bf16_f32 v244, v244, v245
	v_cvt_pk_bf16_f32 v245, v246, v247
	v_lshlrev_b32_e32 v220, 16, v220
	v_lshlrev_b32_e32 v221, 16, v221
	v_mfma_f32_16x16x16_bf16 v[8:11], v[244:245], v[16:17], v[8:11]
	v_lshlrev_b32_e32 v222, 16, v222
	v_lshlrev_b32_e32 v223, 16, v223
	v_pk_mul_f32 v[220:221], v[230:231], v[220:221] op_sel_hi:[0,1]
	v_pk_mul_f32 v[222:223], v[230:231], v[222:223] op_sel_hi:[0,1]
	v_cvt_pk_bf16_f32 v220, v220, v221
	v_cvt_pk_bf16_f32 v221, v222, v223
	s_nop 1
	v_mfma_f32_16x16x16_bf16 v[8:11], v[220:221], v[98:99], v[8:11]
	s_waitcnt lgkmcnt(0)
	ds_read_b128 v[216:219], v182 offset:13760
	ds_read_b32 v230, v57 offset:13760
	ds_read_u16 v244, v49 offset:4704
	ds_read_u16 v245, v49 offset:4848
	ds_read_u16 v246, v49 offset:4992
	ds_read_u16 v247, v49 offset:5136
	ds_read_u16 v220, v49 offset:7008
	ds_read_u16 v221, v49 offset:7152
	ds_read_u16 v222, v49 offset:7296
	ds_read_u16 v223, v49 offset:7440
	v_pk_mul_f32 v[4:5], v[4:5], v[212:213]
	v_pk_mul_f32 v[6:7], v[6:7], v[214:215]
	v_lshlrev_b32_e32 v236, 16, v236
	v_lshlrev_b32_e32 v237, 16, v237
	v_lshlrev_b32_e32 v238, 16, v238
	v_lshlrev_b32_e32 v239, 16, v239
	v_pk_mul_f32 v[236:237], v[228:229], v[236:237] op_sel_hi:[0,1]
	v_pk_mul_f32 v[238:239], v[228:229], v[238:239] op_sel_hi:[0,1]
	v_cvt_pk_bf16_f32 v236, v236, v237
	v_cvt_pk_bf16_f32 v237, v238, v239
	v_lshlrev_b32_e32 v240, 16, v240
	v_lshlrev_b32_e32 v241, 16, v241
	v_mfma_f32_16x16x16_bf16 v[4:7], v[236:237], v[16:17], v[4:7]
	v_lshlrev_b32_e32 v242, 16, v242
	v_lshlrev_b32_e32 v243, 16, v243
	v_pk_mul_f32 v[240:241], v[228:229], v[240:241] op_sel_hi:[0,1]
	v_pk_mul_f32 v[242:243], v[228:229], v[242:243] op_sel_hi:[0,1]
	v_cvt_pk_bf16_f32 v240, v240, v241
	v_cvt_pk_bf16_f32 v241, v242, v243
	s_nop 1
	v_mfma_f32_16x16x16_bf16 v[4:7], v[240:241], v[98:99], v[4:7]
	s_waitcnt lgkmcnt(0)
	v_pk_mul_f32 v[0:1], v[0:1], v[216:217]
	v_pk_mul_f32 v[2:3], v[2:3], v[218:219]
	v_lshlrev_b32_e32 v244, 16, v244
	v_lshlrev_b32_e32 v245, 16, v245
	v_lshlrev_b32_e32 v246, 16, v246
	v_lshlrev_b32_e32 v247, 16, v247
	v_pk_mul_f32 v[244:245], v[230:231], v[244:245] op_sel_hi:[0,1]
	v_pk_mul_f32 v[246:247], v[230:231], v[246:247] op_sel_hi:[0,1]
	v_cvt_pk_bf16_f32 v244, v244, v245
	v_cvt_pk_bf16_f32 v245, v246, v247
	v_lshlrev_b32_e32 v220, 16, v220
	v_lshlrev_b32_e32 v221, 16, v221
	v_mfma_f32_16x16x16_bf16 v[0:3], v[244:245], v[16:17], v[0:3]
	v_lshlrev_b32_e32 v222, 16, v222
	v_lshlrev_b32_e32 v223, 16, v223
	v_pk_mul_f32 v[220:221], v[230:231], v[220:221] op_sel_hi:[0,1]
	v_pk_mul_f32 v[222:223], v[230:231], v[222:223] op_sel_hi:[0,1]
	v_cvt_pk_bf16_f32 v220, v220, v221
	v_cvt_pk_bf16_f32 v221, v222, v223
	s_nop 1
	v_mfma_f32_16x16x16_bf16 v[0:3], v[220:221], v[98:99], v[0:3]
	s_branch .Lkt0_end
.Lkt0_nov:
	s_waitcnt lgkmcnt(0)
	ds_read_b128 v[216:219], v182 offset:13632
	ds_read_b32 v230, v57 offset:13632
	ds_read_u16 v244, v49 offset:4640
	ds_read_u16 v245, v49 offset:4784
	ds_read_u16 v246, v49 offset:4928
	ds_read_u16 v247, v49 offset:5072
	v_pk_mul_f32 v[12:13], v[12:13], v[212:213]
	v_pk_mul_f32 v[14:15], v[14:15], v[214:215]
	v_lshlrev_b32_e32 v236, 16, v236
	v_lshlrev_b32_e32 v237, 16, v237
	v_lshlrev_b32_e32 v238, 16, v238
	v_lshlrev_b32_e32 v239, 16, v239
	v_pk_mul_f32 v[236:237], v[228:229], v[236:237] op_sel_hi:[0,1]
	v_pk_mul_f32 v[238:239], v[228:229], v[238:239] op_sel_hi:[0,1]
	v_cvt_pk_bf16_f32 v236, v236, v237
	v_cvt_pk_bf16_f32 v237, v238, v239
	s_nop 1
	v_mfma_f32_16x16x16_bf16 v[12:15], v[236:237], v[16:17], v[12:15]
	s_waitcnt lgkmcnt(0)
	ds_read_b128 v[212:215], v182 offset:13696
	ds_read_b32 v228, v57 offset:13696
	ds_read_u16 v236, v49 offset:4672
	ds_read_u16 v237, v49 offset:4816
	ds_read_u16 v238, v49 offset:4960
	ds_read_u16 v239, v49 offset:5104
	v_pk_mul_f32 v[8:9], v[8:9], v[216:217]
	v_pk_mul_f32 v[10:11], v[10:11], v[218:219]
	v_lshlrev_b32_e32 v244, 16, v244
	v_lshlrev_b32_e32 v245, 16, v245
	v_lshlrev_b32_e32 v246, 16, v246
	v_lshlrev_b32_e32 v247, 16, v247
	v_pk_mul_f32 v[244:245], v[230:231], v[244:245] op_sel_hi:[0,1]
	v_pk_mul_f32 v[246:247], v[230:231], v[246:247] op_sel_hi:[0,1]
	v_cvt_pk_bf16_f32 v244, v244, v245
	v_cvt_pk_bf16_f32 v245, v246, v247
	s_nop 1
	v_mfma_f32_16x16x16_bf16 v[8:11], v[244:245], v[16:17], v[8:11]
	s_waitcnt lgkmcnt(0)
	ds_read_b128 v[216:219], v182 offset:13760
	ds_read_b32 v230, v57 offset:13760
	ds_read_u16 v244, v49 offset:4704
	ds_read_u16 v245, v49 offset:4848
	ds_read_u16 v246, v49 offset:4992
	ds_read_u16 v247, v49 offset:5136
	v_pk_mul_f32 v[4:5], v[4:5], v[212:213]
	v_pk_mul_f32 v[6:7], v[6:7], v[214:215]
	v_lshlrev_b32_e32 v236, 16, v236
	v_lshlrev_b32_e32 v237, 16, v237
	v_lshlrev_b32_e32 v238, 16, v238
	v_lshlrev_b32_e32 v239, 16, v239
	v_pk_mul_f32 v[236:237], v[228:229], v[236:237] op_sel_hi:[0,1]
	v_pk_mul_f32 v[238:239], v[228:229], v[238:239] op_sel_hi:[0,1]
	v_cvt_pk_bf16_f32 v236, v236, v237
	v_cvt_pk_bf16_f32 v237, v238, v239
	s_nop 1
	v_mfma_f32_16x16x16_bf16 v[4:7], v[236:237], v[16:17], v[4:7]
	s_waitcnt lgkmcnt(0)
	v_pk_mul_f32 v[0:1], v[0:1], v[216:217]
	v_pk_mul_f32 v[2:3], v[2:3], v[218:219]
	v_lshlrev_b32_e32 v244, 16, v244
	v_lshlrev_b32_e32 v245, 16, v245
	v_lshlrev_b32_e32 v246, 16, v246
	v_lshlrev_b32_e32 v247, 16, v247
	v_pk_mul_f32 v[244:245], v[230:231], v[244:245] op_sel_hi:[0,1]
	v_pk_mul_f32 v[246:247], v[230:231], v[246:247] op_sel_hi:[0,1]
	v_cvt_pk_bf16_f32 v244, v244, v245
	v_cvt_pk_bf16_f32 v245, v246, v247
	s_nop 1
	v_mfma_f32_16x16x16_bf16 v[0:3], v[244:245], v[16:17], v[0:3]

.Lktr1:
	v_cndmask_b32_e64 v16, 0, v32, s[24:25]
	v_cndmask_b32_e64 v17, 0, v33, s[30:31]
	v_cndmask_b32_e64 v18, 0, v34, s[34:35]
	v_cndmask_b32_e64 v19, 0, v35, s[36:37]
	v_cvt_pk_bf16_f32 v28, v16, v17
	v_cvt_pk_bf16_f32 v29, v18, v19
	v_cndmask_b32_e64 v20, 0, v36, s[22:23]
	v_cndmask_b32_e64 v21, v37, 0, s[24:25]
	v_cndmask_b32_e64 v22, 0, v38, s[26:27]
	v_cndmask_b32_e64 v23, 0, v39, s[28:29]
	v_cvt_pk_bf16_f32 v16, v24, v25
	v_cvt_pk_bf16_f32 v17, v26, v27
	s_and_b64 vcc, exec, s[40:41]
	s_nop 0
	v_mfma_f32_16x16x16_bf16 v[16:19], v[28:29], v[16:17], v[24:27]
	s_nop 2
	v_cvt_pk_bf16_f32 v24, v20, v21
	v_cvt_pk_bf16_f32 v25, v22, v23
	s_nop 1
	v_mfma_f32_16x16x16_bf16 v[20:23], v[28:29], v[24:25], 0
	v_mfma_f32_16x16x16_bf16 v[24:27], v[24:25], v[28:29], 0
	s_nop 7
	v_cvt_pk_bf16_f32 v24, v24, v25
	v_cvt_pk_bf16_f32 v25, v26, v27
	v_cvt_pk_bf16_f32 v26, v16, v17
	v_cvt_pk_bf16_f32 v27, v18, v19
	s_nop 1
	v_mfma_f32_16x16x16_bf16 v[16:19], v[24:25], v[26:27], v[16:19]
	v_cvt_pk_bf16_f32 v26, v20, v21
	v_cvt_pk_bf16_f32 v27, v22, v23
	s_nop 1
	v_mfma_f32_16x16x16_bf16 v[20:23], v[24:25], v[26:27], 0
	v_mfma_f32_16x16x16_bf16 v[24:27], v[26:27], v[24:25], 0
	s_nop 6
	v_cvt_pk_bf16_f32 v20, v20, v21
	v_cvt_pk_bf16_f32 v21, v22, v23
	v_cvt_pk_bf16_f32 v24, v24, v25
	v_cvt_pk_bf16_f32 v25, v26, v27
	v_cvt_pk_bf16_f32 v26, v16, v17
	v_cvt_pk_bf16_f32 v27, v18, v19
	v_mfma_f32_16x16x16_bf16 v[20:23], v[20:21], v[24:25], 0
	s_nop 0
	v_mfma_f32_16x16x16_bf16 v[16:19], v[24:25], v[26:27], v[16:19]
	s_nop 5
	v_cvt_pk_bf16_f32 v20, v20, v21
	v_cvt_pk_bf16_f32 v21, v22, v23
	v_cvt_pk_bf16_f32 v22, v16, v17
	v_cvt_pk_bf16_f32 v23, v18, v19
	s_nop 1
	v_mfma_f32_16x16x16_bf16 v[16:19], v[20:21], v[22:23], v[16:19]
	s_nop 7
	v_cvt_pk_bf16_f32 v16, v16, v17
	v_cvt_pk_bf16_f32 v17, v18, v19
	s_and_b64 vcc, exec, s[40:41]
	s_cbranch_vccnz .Lkt1_nov
	s_waitcnt lgkmcnt(0)
	ds_read_b128 v[216:219], v182 offset:13632
	ds_read_b32 v230, v57 offset:13632
	ds_read_u16 v244, v49 offset:4640
	ds_read_u16 v245, v49 offset:4784
	ds_read_u16 v246, v49 offset:4928
	ds_read_u16 v247, v49 offset:5072
	ds_read_u16 v220, v49 offset:6944
	ds_read_u16 v221, v49 offset:7088
	ds_read_u16 v222, v49 offset:7232
	ds_read_u16 v223, v49 offset:7376
	v_pk_mul_f32 v[12:13], v[12:13], v[212:213]
	v_pk_mul_f32 v[14:15], v[14:15], v[214:215]
	v_lshlrev_b32_e32 v236, 16, v236
	v_lshlrev_b32_e32 v237, 16, v237
	v_lshlrev_b32_e32 v238, 16, v238
	v_lshlrev_b32_e32 v239, 16, v239
	v_pk_mul_f32 v[236:237], v[228:229], v[236:237] op_sel_hi:[0,1]
	v_pk_mul_f32 v[238:239], v[228:229], v[238:239] op_sel_hi:[0,1]
	v_cvt_pk_bf16_f32 v236, v236, v237
	v_cvt_pk_bf16_f32 v237, v238, v239
	v_lshlrev_b32_e32 v240, 16, v240
	v_lshlrev_b32_e32 v241, 16, v241
	v_mfma_f32_16x16x16_bf16 v[12:15], v[236:237], v[16:17], v[12:15]
	v_lshlrev_b32_e32 v242, 16, v242
	v_lshlrev_b32_e32 v243, 16, v243
	v_pk_mul_f32 v[240:241], v[228:229], v[240:241] op_sel_hi:[0,1]
	v_pk_mul_f32 v[242:243], v[228:229], v[242:243] op_sel_hi:[0,1]
	v_cvt_pk_bf16_f32 v240, v240, v241
	v_cvt_pk_bf16_f32 v241, v242, v243
	s_nop 1
	v_mfma_f32_16x16x16_bf16 v[12:15], v[240:241], v[98:99], v[12:15]
	s_waitcnt lgkmcnt(0)
	ds_read_b128 v[212:215], v182 offset:13696
	ds_read_b32 v228, v57 offset:13696
	ds_read_u16 v236, v49 offset:4672
	ds_read_u16 v237, v49 offset:4816
	ds_read_u16 v238, v49 offset:4960
	ds_read_u16 v239, v49 offset:5104
	ds_read_u16 v240, v49 offset:6976
	ds_read_u16 v241, v49 offset:7120
	ds_read_u16 v242, v49 offset:7264
	ds_read_u16 v243, v49 offset:7408
	v_pk_mul_f32 v[8:9], v[8:9], v[216:217]
	v_pk_mul_f32 v[10:11], v[10:11], v[218:219]
	v_lshlrev_b32_e32 v244, 16, v244
	v_lshlrev_b32_e32 v245, 16, v245
	v_lshlrev_b32_e32 v246, 16, v246
	v_lshlrev_b32_e32 v247, 16, v247
	v_pk_mul_f32 v[244:245], v[230:231], v[244:245] op_sel_hi:[0,1]
	v_pk_mul_f32 v[246:247], v[230:231], v[246:247] op_sel_hi:[0,1]
	v_cvt_pk_bf16_f32 v244, v244, v245
	v_cvt_pk_bf16_f32 v245, v246, v247
	v_lshlrev_b32_e32 v220, 16, v220
	v_lshlrev_b32_e32 v221, 16, v221
	v_mfma_f32_16x16x16_bf16 v[8:11], v[244:245], v[16:17], v[8:11]
	v_lshlrev_b32_e32 v222, 16, v222
	v_lshlrev_b32_e32 v223, 16, v223
	v_pk_mul_f32 v[220:221], v[230:231], v[220:221] op_sel_hi:[0,1]
	v_pk_mul_f32 v[222:223], v[230:231], v[222:223] op_sel_hi:[0,1]
	v_cvt_pk_bf16_f32 v220, v220, v221
	v_cvt_pk_bf16_f32 v221, v222, v223
	s_nop 1
	v_mfma_f32_16x16x16_bf16 v[8:11], v[220:221], v[98:99], v[8:11]
	s_waitcnt lgkmcnt(0)
	ds_read_b128 v[216:219], v182 offset:13760
	ds_read_b32 v230, v57 offset:13760
	ds_read_u16 v244, v49 offset:4704
	ds_read_u16 v245, v49 offset:4848
	ds_read_u16 v246, v49 offset:4992
	ds_read_u16 v247, v49 offset:5136
	ds_read_u16 v220, v49 offset:7008
	ds_read_u16 v221, v49 offset:7152
	ds_read_u16 v222, v49 offset:7296
	ds_read_u16 v223, v49 offset:7440
	v_pk_mul_f32 v[4:5], v[4:5], v[212:213]
	v_pk_mul_f32 v[6:7], v[6:7], v[214:215]
	v_lshlrev_b32_e32 v236, 16, v236
	v_lshlrev_b32_e32 v237, 16, v237
	v_lshlrev_b32_e32 v238, 16, v238
	v_lshlrev_b32_e32 v239, 16, v239
	v_pk_mul_f32 v[236:237], v[228:229], v[236:237] op_sel_hi:[0,1]
	v_pk_mul_f32 v[238:239], v[228:229], v[238:239] op_sel_hi:[0,1]
	v_cvt_pk_bf16_f32 v236, v236, v237
	v_cvt_pk_bf16_f32 v237, v238, v239
	v_lshlrev_b32_e32 v240, 16, v240
	v_lshlrev_b32_e32 v241, 16, v241
	v_mfma_f32_16x16x16_bf16 v[4:7], v[236:237], v[16:17], v[4:7]
	v_lshlrev_b32_e32 v242, 16, v242
	v_lshlrev_b32_e32 v243, 16, v243
	v_pk_mul_f32 v[240:241], v[228:229], v[240:241] op_sel_hi:[0,1]
	v_pk_mul_f32 v[242:243], v[228:229], v[242:243] op_sel_hi:[0,1]
	v_cvt_pk_bf16_f32 v240, v240, v241
	v_cvt_pk_bf16_f32 v241, v242, v243
	s_nop 1
	v_mfma_f32_16x16x16_bf16 v[4:7], v[240:241], v[98:99], v[4:7]
	s_waitcnt lgkmcnt(0)
	v_pk_mul_f32 v[0:1], v[0:1], v[216:217]
	v_pk_mul_f32 v[2:3], v[2:3], v[218:219]
	v_lshlrev_b32_e32 v244, 16, v244
	v_lshlrev_b32_e32 v245, 16, v245
	v_lshlrev_b32_e32 v246, 16, v246
	v_lshlrev_b32_e32 v247, 16, v247
	v_pk_mul_f32 v[244:245], v[230:231], v[244:245] op_sel_hi:[0,1]
	v_pk_mul_f32 v[246:247], v[230:231], v[246:247] op_sel_hi:[0,1]
	v_cvt_pk_bf16_f32 v244, v244, v245
	v_cvt_pk_bf16_f32 v245, v246, v247
	v_lshlrev_b32_e32 v220, 16, v220
	v_lshlrev_b32_e32 v221, 16, v221
	v_mfma_f32_16x16x16_bf16 v[0:3], v[244:245], v[16:17], v[0:3]
	v_lshlrev_b32_e32 v222, 16, v222
	v_lshlrev_b32_e32 v223, 16, v223
	v_pk_mul_f32 v[220:221], v[230:231], v[220:221] op_sel_hi:[0,1]
	v_pk_mul_f32 v[222:223], v[230:231], v[222:223] op_sel_hi:[0,1]
	v_cvt_pk_bf16_f32 v220, v220, v221
	v_cvt_pk_bf16_f32 v221, v222, v223
	s_nop 1
	v_mfma_f32_16x16x16_bf16 v[0:3], v[220:221], v[98:99], v[0:3]
	s_branch .Lkt1_end
